# b_w_in / b_w_out conversion moved from the down-proj tail to the out-proj tail (overlaps the K-split unit phase there; down-proj tail now conversion-free)
# baseline (speedup 1.0000x reference)
.LBB0_810:
	v_readlane_b32 s10, v248, 10
	s_and_b64 s[4:5], s[24:25], exec
	s_movk_i32 s8, 0x7a00
	v_readlane_b32 s11, v248, 11
	s_cselect_b32 s6, 0x4c00, s8
	s_and_b64 s[4:5], s[10:11], exec
	s_cselect_b32 s4, s6, 0xa600
	s_and_b64 s[6:7], s[24:25], exec
	s_mov_b32 s6, 0xbc00
	s_cselect_b32 s5, s8, 0x7a00
	s_cselect_b32 s8, s6, 0xa600
	s_and_b64 s[6:7], s[10:11], exec
	s_cselect_b32 s8, s5, s8
	s_cmp_lt_u32 s4, s8
	v_readlane_b32 s10, v249, 50
	s_cselect_b64 s[6:7], -1, 0
	v_readlane_b32 s11, v249, 51
	s_and_b64 s[6:7], s[10:11], s[6:7]
	s_andn2_b64 vcc, exec, s[6:7]
	s_movk_i32 s53, 0x1000
	s_cbranch_vccnz .LBB0_874
	v_mov_b32_e32 v16, v182
	v_readlane_b32 s6, v248, 0
	v_readfirstlane_b32 s5, v16
	s_ashr_i32 s5, s5, 6
	s_add_i32 s6, s6, s4
	s_add_i32 s9, s6, s5
	s_cmp_ge_i32 s9, s8
	s_cbranch_scc1 .LBB0_874
	v_lshlrev_b32_e32 v0, 3, v16
	v_and_b32_e32 v0, 56, v0
	v_lshlrev_b32_e32 v144, 1, v0
	s_mul_i32 s10, s5, 0x2100
	v_bfe_u32 v35, v16, 3, 3
	v_mul_u32_u24_e32 v4, 0x84, v0
	v_lshl_add_u64 v[0:1], s[26:27], 0, v[144:145]
	s_mov_b64 s[6:7], 0xa600000
	s_add_i32 s11, s10, 0
	v_lshl_add_u64 v[2:3], v[0:1], 0, s[6:7]
	v_lshlrev_b32_e32 v5, 2, v35
	s_mov_b64 s[6:7], 0x6400000
	v_add3_u32 v36, s11, v4, v5
	v_lshl_add_u64 v[4:5], v[0:1], 0, s[6:7]
	s_mov_b64 s[6:7], 0x3000000
	v_lshl_add_u64 v[6:7], v[0:1], 0, s[6:7]
	s_mov_b64 s[6:7], 0x2000000
	v_lshl_add_u64 v[8:9], v[0:1], 0, s[6:7]
	s_mov_b64 s[6:7], 0x9000000
	v_lshl_add_u64 v[10:11], v[0:1], 0, s[6:7]
	s_mov_b64 s[6:7], 0x3800000
	v_lshl_add_u64 v[12:13], v[0:1], 0, s[6:7]
	s_mov_b64 s[6:7], 0x1800000
	v_lshl_add_u64 v[14:15], v[0:1], 0, s[6:7]
	v_readlane_b32 s6, v249, 61
	s_add_i32 s6, s6, s4
	s_add_i32 s11, s6, s5
	v_readlane_b32 s6, v249, 62
	s_add_i32 s6, s6, s4
	s_add_i32 s16, s6, s5
	v_readlane_b32 s6, v249, 63
	v_bfe_u32 v34, v16, 5, 1
	s_add_i32 s6, s6, s4
	v_mul_u32_u24_e32 v17, 0x84, v34
	v_lshlrev_b32_e32 v16, 2, v16
	s_add_i32 s17, s6, s5
	v_readlane_b32 s6, v248, 1
	v_or_b32_e32 v17, s10, v17
	v_and_b32_e32 v16, 0x7c, v16
	s_add_i32 s4, s6, s4
	v_or_b32_e32 v37, 8, v35
	v_or_b32_e32 v38, 16, v35
	v_or_b32_e32 v39, 24, v35
	v_add3_u32 v40, v17, v16, 0
	v_mov_b32_e32 v17, v145
	v_or_b32_e32 v41, 0xffff5a0e, v34
	s_lshl_b32 s10, s9, 5
	v_or_b32_e32 v42, 0xffff5a0c, v34
	v_or_b32_e32 v43, 0xffff5a0a, v34
	v_or_b32_e32 v44, 0xffff5a08, v34
	v_or_b32_e32 v45, 0xffff5a06, v34
	v_or_b32_e32 v46, 0xffff5a04, v34
	v_or_b32_e32 v47, 0xffff5a02, v34
	v_or_b32_e32 v48, 0xffff5a00, v34
	v_or_b32_e32 v49, 14, v34
	v_or_b32_e32 v50, 12, v34
	v_or_b32_e32 v51, 10, v34
	v_or_b32_e32 v52, 8, v34
	v_or_b32_e32 v53, 6, v34
	v_or_b32_e32 v54, 4, v34
	v_or_b32_e32 v55, 2, v34
	s_add_i32 s18, s4, s5
	s_branch .LBB0_814
